# moba_gate: workgroup-level aggregation of list-append atomics through LDS counters (one global atomic per WG and block instead of per wave)
# speedup vs baseline: 1.0416x; 1.0416x over previous
.LBB0_1002:
	s_or_b64 exec, exec, s[0:1]
	v_readlane_b32 s0, v255, 4
	v_readlane_b32 s1, v255, 5
	s_and_b64 vcc, exec, s[0:1]
	s_mov_b32 s17, s86
	v_and_b32_e32 v56, 15, v211
	v_lshlrev_b32_e32 v56, 2, v56
	v_mov_b32_e32 v2, 0
	ds_write_b32 v56, v2 offset:12288
	s_cbranch_vccz .LBB0_1017

.LBB0_1027:
	s_or_b64 exec, exec, s[0:1]
	v_cndmask_b32_e64 v4, 0, 1, s[44:45]
	s_lshl_b32 s2, s6, 4
	v_cmp_ne_u32_e64 s[42:43], 1, v4
	v_and_b32_e32 v4, 1, v8
	v_and_b32_e32 v0, 63, v56
	s_ashr_i32 s3, s2, 31
	v_mov_b32_e32 v3, 0
	s_andn2_b64 vcc, exec, s[44:45]
	v_cmp_eq_u32_e64 s[0:1], 1, v4
	v_mov_b32_e32 v7, 0
	s_cbranch_vccnz .LBB0_1033
	s_and_b64 s[0:1], s[40:41], s[0:1]
	v_cndmask_b32_e64 v5, 0, 1, s[0:1]
	v_cmp_ne_u32_e32 vcc, 0, v5
	s_cmp_lg_u64 vcc, 0
	s_ff1_i32_b64 s0, vcc
	s_cselect_b64 s[6:7], -1, 0
	v_cmp_eq_u32_e64 s[0:1], s0, v0
	v_mov_b32_e32 v7, 0
	s_and_b64 s[6:7], s[6:7], s[0:1]
	s_and_saveexec_b64 s[0:1], s[6:7]
	s_cbranch_execz .LBB0_1032
	s_mov_b64 s[44:45], exec
	v_mbcnt_lo_u32_b32 v5, s44, 0
	v_mbcnt_hi_u32_b32 v5, s45, v5
	s_bcnt1_i32_b64 s18, vcc
	v_cmp_eq_u32_e32 vcc, 0, v5
	s_and_saveexec_b64 s[6:7], vcc
	s_cbranch_execz .LBB0_1031
	s_lshl_b64 s[66:67], s[2:3], 2
	v_readlane_b32 s68, v253, 15
	v_readlane_b32 s69, v253, 16
	s_add_u32 s66, s68, s66
	s_addc_u32 s67, s69, s67
	s_bcnt1_i32_b64 s19, s[44:45]
	s_mul_i32 s19, s18, s19
	v_mov_b32_e32 v6, s19
	v_mov_b32_e32 v5, 12288
	ds_add_rtn_u32 v7, v5, v6
.LBB0_1031:
	s_or_b64 exec, exec, s[6:7]
.LBB0_1032:
	s_or_b64 exec, exec, s[0:1]
.LBB0_1033:
	v_cndmask_b32_e64 v5, 0, 1, s[46:47]
	v_and_b32_e32 v6, 2, v8
	v_cmp_ne_u32_e64 s[44:45], 1, v5
	s_andn2_b64 vcc, exec, s[46:47]
	v_cmp_ne_u32_e64 s[0:1], 0, v6
	s_cbranch_vccnz .LBB0_1039
	s_and_b64 s[0:1], s[40:41], s[0:1]
	v_cndmask_b32_e64 v5, 0, 1, s[0:1]
	v_cmp_ne_u32_e32 vcc, 0, v5
	s_cmp_lg_u64 vcc, 0
	s_ff1_i32_b64 s0, vcc
	s_cselect_b64 s[6:7], -1, 0
	v_cmp_eq_u32_e64 s[0:1], s0, v0
	v_mov_b32_e32 v3, 0
	s_and_b64 s[6:7], s[6:7], s[0:1]
	s_and_saveexec_b64 s[0:1], s[6:7]
	s_cbranch_execz .LBB0_1038
	s_mov_b64 s[46:47], exec
	v_mbcnt_lo_u32_b32 v3, s46, 0
	v_mbcnt_hi_u32_b32 v3, s47, v3
	s_bcnt1_i32_b64 s18, vcc
	v_cmp_eq_u32_e32 vcc, 0, v3
	s_and_saveexec_b64 s[6:7], vcc
	s_cbranch_execz .LBB0_1037
	s_lshl_b64 s[66:67], s[2:3], 2
	s_add_u32 s66, s92, s66
	s_addc_u32 s67, s93, s67
	s_bcnt1_i32_b64 s19, s[46:47]
	s_mul_i32 s19, s18, s19
	v_mov_b32_e32 v5, s19
	v_mov_b32_e32 v3, 12292
	ds_add_rtn_u32 v3, v3, v5
.LBB0_1037:
	s_or_b64 exec, exec, s[6:7]
.LBB0_1038:
	s_or_b64 exec, exec, s[0:1]
.LBB0_1039:
	v_cndmask_b32_e64 v9, 0, 1, s[48:49]
	v_cmp_ne_u32_e64 s[46:47], 1, v9
	v_and_b32_e32 v9, 4, v8
	v_mov_b32_e32 v5, 0
	s_andn2_b64 vcc, exec, s[48:49]
	v_cmp_ne_u32_e64 s[0:1], 0, v9
	v_mov_b32_e32 v12, 0
	s_cbranch_vccnz .LBB0_1045
	s_and_b64 s[0:1], s[40:41], s[0:1]
	v_cndmask_b32_e64 v10, 0, 1, s[0:1]
	v_cmp_ne_u32_e32 vcc, 0, v10
	s_cmp_lg_u64 vcc, 0
	s_ff1_i32_b64 s0, vcc
	s_cselect_b64 s[6:7], -1, 0
	v_cmp_eq_u32_e64 s[0:1], s0, v0
	v_mov_b32_e32 v12, 0
	s_and_b64 s[6:7], s[6:7], s[0:1]
	s_and_saveexec_b64 s[0:1], s[6:7]
	s_cbranch_execz .LBB0_1044
	s_mov_b64 s[48:49], exec
	v_mbcnt_lo_u32_b32 v10, s48, 0
	v_mbcnt_hi_u32_b32 v10, s49, v10
	s_bcnt1_i32_b64 s18, vcc
	v_cmp_eq_u32_e32 vcc, 0, v10
	s_and_saveexec_b64 s[6:7], vcc
	s_cbranch_execz .LBB0_1043
	s_lshl_b64 s[66:67], s[2:3], 2
	s_add_u32 s66, s92, s66
	s_addc_u32 s67, s93, s67
	s_bcnt1_i32_b64 s19, s[48:49]
	s_mul_i32 s19, s18, s19
	v_mov_b32_e32 v11, s19
	v_mov_b32_e32 v10, 12296
	ds_add_rtn_u32 v12, v10, v11
.LBB0_1043:
	s_or_b64 exec, exec, s[6:7]
.LBB0_1044:
	s_or_b64 exec, exec, s[0:1]
.LBB0_1045:
	v_cndmask_b32_e64 v10, 0, 1, s[50:51]
	v_and_b32_e32 v11, 8, v8
	v_cmp_ne_u32_e64 s[48:49], 1, v10
	s_andn2_b64 vcc, exec, s[50:51]
	v_cmp_ne_u32_e64 s[0:1], 0, v11
	s_cbranch_vccnz .LBB0_1051
	s_and_b64 s[0:1], s[40:41], s[0:1]
	v_cndmask_b32_e64 v10, 0, 1, s[0:1]
	v_cmp_ne_u32_e32 vcc, 0, v10
	s_cmp_lg_u64 vcc, 0
	s_ff1_i32_b64 s0, vcc
	s_cselect_b64 s[6:7], -1, 0
	v_cmp_eq_u32_e64 s[0:1], s0, v0
	v_mov_b32_e32 v5, 0
	s_and_b64 s[6:7], s[6:7], s[0:1]
	s_and_saveexec_b64 s[0:1], s[6:7]
	s_cbranch_execz .LBB0_1050
	s_mov_b64 s[50:51], exec
	v_mbcnt_lo_u32_b32 v5, s50, 0
	v_mbcnt_hi_u32_b32 v5, s51, v5
	s_bcnt1_i32_b64 s18, vcc
	v_cmp_eq_u32_e32 vcc, 0, v5
	s_and_saveexec_b64 s[6:7], vcc
	s_cbranch_execz .LBB0_1049
	s_lshl_b64 s[66:67], s[2:3], 2
	s_add_u32 s66, s92, s66
	s_addc_u32 s67, s93, s67
	s_bcnt1_i32_b64 s19, s[50:51]
	s_mul_i32 s19, s18, s19
	v_mov_b32_e32 v10, s19
	v_mov_b32_e32 v5, 12300
	ds_add_rtn_u32 v5, v5, v10
.LBB0_1049:
	s_or_b64 exec, exec, s[6:7]
.LBB0_1050:
	s_or_b64 exec, exec, s[0:1]
.LBB0_1051:
	v_cndmask_b32_e64 v13, 0, 1, s[52:53]
	v_cmp_ne_u32_e64 s[50:51], 1, v13
	v_and_b32_e32 v13, 16, v8
	v_mov_b32_e32 v10, 0
	s_andn2_b64 vcc, exec, s[52:53]
	v_cmp_ne_u32_e64 s[0:1], 0, v13
	v_mov_b32_e32 v16, 0
	s_cbranch_vccnz .LBB0_1057
	s_and_b64 s[0:1], s[40:41], s[0:1]
	v_cndmask_b32_e64 v14, 0, 1, s[0:1]
	v_cmp_ne_u32_e32 vcc, 0, v14
	s_cmp_lg_u64 vcc, 0
	s_ff1_i32_b64 s0, vcc
	s_cselect_b64 s[6:7], -1, 0
	v_cmp_eq_u32_e64 s[0:1], s0, v0
	v_mov_b32_e32 v16, 0
	s_and_b64 s[6:7], s[6:7], s[0:1]
	s_and_saveexec_b64 s[0:1], s[6:7]
	s_cbranch_execz .LBB0_1056
	s_mov_b64 s[52:53], exec
	v_mbcnt_lo_u32_b32 v14, s52, 0
	v_mbcnt_hi_u32_b32 v14, s53, v14
	s_bcnt1_i32_b64 s18, vcc
	v_cmp_eq_u32_e32 vcc, 0, v14
	s_and_saveexec_b64 s[6:7], vcc
	s_cbranch_execz .LBB0_1055
	s_lshl_b64 s[66:67], s[2:3], 2
	s_add_u32 s66, s92, s66
	s_addc_u32 s67, s93, s67
	s_bcnt1_i32_b64 s19, s[52:53]
	s_mul_i32 s19, s18, s19
	v_mov_b32_e32 v15, s19
	v_mov_b32_e32 v14, 12304
	ds_add_rtn_u32 v16, v14, v15
.LBB0_1055:
	s_or_b64 exec, exec, s[6:7]
.LBB0_1056:
	s_or_b64 exec, exec, s[0:1]
.LBB0_1057:
	v_cndmask_b32_e64 v14, 0, 1, s[54:55]
	v_and_b32_e32 v15, 32, v8
	v_cmp_ne_u32_e64 s[52:53], 1, v14
	s_andn2_b64 vcc, exec, s[54:55]
	v_cmp_ne_u32_e64 s[0:1], 0, v15
	s_cbranch_vccnz .LBB0_1063
	s_and_b64 s[0:1], s[40:41], s[0:1]
	v_cndmask_b32_e64 v14, 0, 1, s[0:1]
	v_cmp_ne_u32_e32 vcc, 0, v14
	s_cmp_lg_u64 vcc, 0
	s_ff1_i32_b64 s0, vcc
	s_cselect_b64 s[6:7], -1, 0
	v_cmp_eq_u32_e64 s[0:1], s0, v0
	v_mov_b32_e32 v10, 0
	s_and_b64 s[6:7], s[6:7], s[0:1]
	s_and_saveexec_b64 s[0:1], s[6:7]
	s_cbranch_execz .LBB0_1062
	s_mov_b64 s[54:55], exec
	v_mbcnt_lo_u32_b32 v10, s54, 0
	v_mbcnt_hi_u32_b32 v10, s55, v10
	s_bcnt1_i32_b64 s18, vcc
	v_cmp_eq_u32_e32 vcc, 0, v10
	s_and_saveexec_b64 s[6:7], vcc
	s_cbranch_execz .LBB0_1061
	s_lshl_b64 s[66:67], s[2:3], 2
	s_add_u32 s66, s92, s66
	s_addc_u32 s67, s93, s67
	s_bcnt1_i32_b64 s19, s[54:55]
	s_mul_i32 s19, s18, s19
	v_mov_b32_e32 v14, s19
	v_mov_b32_e32 v10, 12308
	ds_add_rtn_u32 v10, v10, v14
.LBB0_1061:
	s_or_b64 exec, exec, s[6:7]
.LBB0_1062:
	s_or_b64 exec, exec, s[0:1]
.LBB0_1063:
	v_cndmask_b32_e64 v17, 0, 1, s[56:57]
	v_cmp_ne_u32_e64 s[54:55], 1, v17
	v_and_b32_e32 v17, 64, v8
	v_mov_b32_e32 v14, 0
	s_andn2_b64 vcc, exec, s[56:57]
	v_cmp_ne_u32_e64 s[0:1], 0, v17
	v_mov_b32_e32 v20, 0
	s_cbranch_vccnz .LBB0_1069
	s_and_b64 s[0:1], s[40:41], s[0:1]
	v_cndmask_b32_e64 v18, 0, 1, s[0:1]
	v_cmp_ne_u32_e32 vcc, 0, v18
	s_cmp_lg_u64 vcc, 0
	s_ff1_i32_b64 s0, vcc
	s_cselect_b64 s[6:7], -1, 0
	v_cmp_eq_u32_e64 s[0:1], s0, v0
	v_mov_b32_e32 v20, 0
	s_and_b64 s[6:7], s[6:7], s[0:1]
	s_and_saveexec_b64 s[0:1], s[6:7]
	s_cbranch_execz .LBB0_1068
	s_mov_b64 s[56:57], exec
	v_mbcnt_lo_u32_b32 v18, s56, 0
	v_mbcnt_hi_u32_b32 v18, s57, v18
	s_bcnt1_i32_b64 s18, vcc
	v_cmp_eq_u32_e32 vcc, 0, v18
	s_and_saveexec_b64 s[6:7], vcc
	s_cbranch_execz .LBB0_1067
	s_lshl_b64 s[66:67], s[2:3], 2
	s_add_u32 s66, s92, s66
	s_addc_u32 s67, s93, s67
	s_bcnt1_i32_b64 s19, s[56:57]
	s_mul_i32 s19, s18, s19
	v_mov_b32_e32 v19, s19
	v_mov_b32_e32 v18, 12312
	ds_add_rtn_u32 v20, v18, v19
.LBB0_1067:
	s_or_b64 exec, exec, s[6:7]
.LBB0_1068:
	s_or_b64 exec, exec, s[0:1]
.LBB0_1069:
	v_cndmask_b32_e64 v18, 0, 1, s[58:59]
	v_and_b32_e32 v19, 0x80, v8
	v_cmp_ne_u32_e64 s[56:57], 1, v18
	s_andn2_b64 vcc, exec, s[58:59]
	v_cmp_ne_u32_e64 s[0:1], 0, v19
	s_cbranch_vccnz .LBB0_1075
	s_and_b64 s[0:1], s[40:41], s[0:1]
	v_cndmask_b32_e64 v18, 0, 1, s[0:1]
	v_cmp_ne_u32_e32 vcc, 0, v18
	s_cmp_lg_u64 vcc, 0
	s_ff1_i32_b64 s0, vcc
	s_cselect_b64 s[6:7], -1, 0
	v_cmp_eq_u32_e64 s[0:1], s0, v0
	v_mov_b32_e32 v14, 0
	s_and_b64 s[6:7], s[6:7], s[0:1]
	s_and_saveexec_b64 s[0:1], s[6:7]
	s_cbranch_execz .LBB0_1074
	s_mov_b64 s[58:59], exec
	v_mbcnt_lo_u32_b32 v14, s58, 0
	v_mbcnt_hi_u32_b32 v14, s59, v14
	s_bcnt1_i32_b64 s18, vcc
	v_cmp_eq_u32_e32 vcc, 0, v14
	s_and_saveexec_b64 s[6:7], vcc
	s_cbranch_execz .LBB0_1073
	s_lshl_b64 s[66:67], s[2:3], 2
	s_add_u32 s66, s92, s66
	s_addc_u32 s67, s93, s67
	s_bcnt1_i32_b64 s19, s[58:59]
	s_mul_i32 s19, s18, s19
	v_mov_b32_e32 v18, s19
	v_mov_b32_e32 v14, 12316
	ds_add_rtn_u32 v14, v14, v18
.LBB0_1073:
	s_or_b64 exec, exec, s[6:7]
.LBB0_1074:
	s_or_b64 exec, exec, s[0:1]
.LBB0_1075:
	v_cndmask_b32_e64 v21, 0, 1, s[60:61]
	v_cmp_ne_u32_e64 s[58:59], 1, v21
	v_and_b32_e32 v21, 0x100, v8
	v_mov_b32_e32 v18, 0
	s_andn2_b64 vcc, exec, s[60:61]
	v_cmp_ne_u32_e64 s[0:1], 0, v21
	v_mov_b32_e32 v24, 0
	s_cbranch_vccnz .LBB0_1081
	s_and_b64 s[0:1], s[40:41], s[0:1]
	v_cndmask_b32_e64 v22, 0, 1, s[0:1]
	v_cmp_ne_u32_e32 vcc, 0, v22
	s_cmp_lg_u64 vcc, 0
	s_ff1_i32_b64 s0, vcc
	s_cselect_b64 s[6:7], -1, 0
	v_cmp_eq_u32_e64 s[0:1], s0, v0
	v_mov_b32_e32 v24, 0
	s_and_b64 s[6:7], s[6:7], s[0:1]
	s_and_saveexec_b64 s[0:1], s[6:7]
	s_cbranch_execz .LBB0_1080
	s_mov_b64 s[60:61], exec
	v_mbcnt_lo_u32_b32 v22, s60, 0
	v_mbcnt_hi_u32_b32 v22, s61, v22
	s_bcnt1_i32_b64 s18, vcc
	v_cmp_eq_u32_e32 vcc, 0, v22
	s_and_saveexec_b64 s[6:7], vcc
	s_cbranch_execz .LBB0_1079
	s_lshl_b64 s[66:67], s[2:3], 2
	s_add_u32 s66, s92, s66
	s_addc_u32 s67, s93, s67
	s_bcnt1_i32_b64 s19, s[60:61]
	s_mul_i32 s19, s18, s19
	v_mov_b32_e32 v23, s19
	v_mov_b32_e32 v22, 12320
	ds_add_rtn_u32 v24, v22, v23
.LBB0_1079:
	s_or_b64 exec, exec, s[6:7]
.LBB0_1080:
	s_or_b64 exec, exec, s[0:1]
.LBB0_1081:
	v_cndmask_b32_e64 v22, 0, 1, s[62:63]
	v_and_b32_e32 v23, 0x200, v8
	v_cmp_ne_u32_e64 s[60:61], 1, v22
	s_andn2_b64 vcc, exec, s[62:63]
	v_cmp_ne_u32_e64 s[0:1], 0, v23
	s_cbranch_vccnz .LBB0_1087
	s_and_b64 s[0:1], s[40:41], s[0:1]
	v_cndmask_b32_e64 v22, 0, 1, s[0:1]
	v_cmp_ne_u32_e32 vcc, 0, v22
	s_cmp_lg_u64 vcc, 0
	s_ff1_i32_b64 s0, vcc
	s_cselect_b64 s[6:7], -1, 0
	v_cmp_eq_u32_e64 s[0:1], s0, v0
	v_mov_b32_e32 v18, 0
	s_and_b64 s[6:7], s[6:7], s[0:1]
	s_and_saveexec_b64 s[0:1], s[6:7]
	s_cbranch_execz .LBB0_1086
	s_mov_b64 s[62:63], exec
	v_mbcnt_lo_u32_b32 v18, s62, 0
	v_mbcnt_hi_u32_b32 v18, s63, v18
	s_bcnt1_i32_b64 s18, vcc
	v_cmp_eq_u32_e32 vcc, 0, v18
	s_and_saveexec_b64 s[6:7], vcc
	s_cbranch_execz .LBB0_1085
	s_lshl_b64 s[66:67], s[2:3], 2
	s_add_u32 s66, s92, s66
	s_addc_u32 s67, s93, s67
	s_bcnt1_i32_b64 s19, s[62:63]
	s_mul_i32 s19, s18, s19
	v_mov_b32_e32 v22, s19
	v_mov_b32_e32 v18, 12324
	ds_add_rtn_u32 v18, v18, v22
.LBB0_1085:
	s_or_b64 exec, exec, s[6:7]
.LBB0_1086:
	s_or_b64 exec, exec, s[0:1]
.LBB0_1087:
	v_cndmask_b32_e64 v25, 0, 1, s[64:65]
	v_cmp_ne_u32_e64 s[62:63], 1, v25
	v_and_b32_e32 v25, 0x400, v8
	v_mov_b32_e32 v22, 0
	s_andn2_b64 vcc, exec, s[64:65]
	v_cmp_ne_u32_e64 s[0:1], 0, v25
	v_mov_b32_e32 v28, 0
	s_cbranch_vccnz .LBB0_1093
	s_and_b64 s[0:1], s[40:41], s[0:1]
	v_cndmask_b32_e64 v26, 0, 1, s[0:1]
	v_cmp_ne_u32_e32 vcc, 0, v26
	s_cmp_lg_u64 vcc, 0
	s_ff1_i32_b64 s0, vcc
	s_cselect_b64 s[6:7], -1, 0
	v_cmp_eq_u32_e64 s[0:1], s0, v0
	v_mov_b32_e32 v28, 0
	s_and_b64 s[6:7], s[6:7], s[0:1]
	s_and_saveexec_b64 s[0:1], s[6:7]
	s_cbranch_execz .LBB0_1092
	s_mov_b64 s[64:65], exec
	v_mbcnt_lo_u32_b32 v26, s64, 0
	v_mbcnt_hi_u32_b32 v26, s65, v26
	s_bcnt1_i32_b64 s18, vcc
	v_cmp_eq_u32_e32 vcc, 0, v26
	s_and_saveexec_b64 s[6:7], vcc
	s_cbranch_execz .LBB0_1091
	s_lshl_b64 s[66:67], s[2:3], 2
	s_add_u32 s66, s92, s66
	s_addc_u32 s67, s93, s67
	s_bcnt1_i32_b64 s19, s[64:65]
	s_mul_i32 s19, s18, s19
	v_mov_b32_e32 v27, s19
	v_mov_b32_e32 v26, 12328
	ds_add_rtn_u32 v28, v26, v27
.LBB0_1091:
	s_or_b64 exec, exec, s[6:7]
.LBB0_1092:
	s_or_b64 exec, exec, s[0:1]
.LBB0_1093:
	v_cndmask_b32_e64 v26, 0, 1, s[38:39]
	v_and_b32_e32 v27, 0x800, v8
	v_cmp_ne_u32_e64 s[64:65], 1, v26
	s_andn2_b64 vcc, exec, s[38:39]
	v_cmp_ne_u32_e64 s[0:1], 0, v27
	s_cbranch_vccnz .LBB0_1099
	s_and_b64 s[0:1], s[40:41], s[0:1]
	v_cndmask_b32_e64 v26, 0, 1, s[0:1]
	v_cmp_ne_u32_e32 vcc, 0, v26
	s_cmp_lg_u64 vcc, 0
	s_ff1_i32_b64 s0, vcc
	s_cselect_b64 s[6:7], -1, 0
	v_cmp_eq_u32_e64 s[0:1], s0, v0
	v_mov_b32_e32 v22, 0
	s_and_b64 s[6:7], s[6:7], s[0:1]
	s_and_saveexec_b64 s[0:1], s[6:7]
	s_cbranch_execz .LBB0_1098
	s_mov_b64 s[38:39], exec
	v_mbcnt_lo_u32_b32 v22, s38, 0
	v_mbcnt_hi_u32_b32 v22, s39, v22
	s_bcnt1_i32_b64 s18, vcc
	v_cmp_eq_u32_e32 vcc, 0, v22
	s_and_saveexec_b64 s[6:7], vcc
	s_cbranch_execz .LBB0_1097
	s_lshl_b64 s[66:67], s[2:3], 2
	s_add_u32 s66, s92, s66
	s_addc_u32 s67, s93, s67
	s_bcnt1_i32_b64 s19, s[38:39]
	s_mul_i32 s19, s18, s19
	v_mov_b32_e32 v26, s19
	v_mov_b32_e32 v22, 12332
	ds_add_rtn_u32 v22, v22, v26
.LBB0_1097:
	s_or_b64 exec, exec, s[6:7]
.LBB0_1098:
	s_or_b64 exec, exec, s[0:1]
.LBB0_1099:
	v_cndmask_b32_e64 v29, 0, 1, s[36:37]
	v_cmp_ne_u32_e64 s[66:67], 1, v29
	v_and_b32_e32 v29, 0x1000, v8
	v_mov_b32_e32 v26, 0
	s_andn2_b64 vcc, exec, s[36:37]
	v_cmp_ne_u32_e64 s[0:1], 0, v29
	v_mov_b32_e32 v31, 0
	s_cbranch_vccnz .LBB0_1105
	s_and_b64 s[0:1], s[40:41], s[0:1]
	v_cndmask_b32_e64 v30, 0, 1, s[0:1]
	v_cmp_ne_u32_e32 vcc, 0, v30
	s_cmp_lg_u64 vcc, 0
	s_ff1_i32_b64 s0, vcc
	s_cselect_b64 s[6:7], -1, 0
	v_cmp_eq_u32_e64 s[0:1], s0, v0
	v_mov_b32_e32 v31, 0
	s_and_b64 s[6:7], s[6:7], s[0:1]
	s_and_saveexec_b64 s[0:1], s[6:7]
	s_cbranch_execz .LBB0_1104
	s_mov_b64 s[36:37], exec
	v_mbcnt_lo_u32_b32 v30, s36, 0
	v_mbcnt_hi_u32_b32 v30, s37, v30
	s_bcnt1_i32_b64 s18, vcc
	v_cmp_eq_u32_e32 vcc, 0, v30
	s_and_saveexec_b64 s[6:7], vcc
	s_cbranch_execz .LBB0_1103
	s_lshl_b64 s[38:39], s[2:3], 2
	s_add_u32 s38, s92, s38
	s_addc_u32 s39, s93, s39
	s_bcnt1_i32_b64 s19, s[36:37]
	s_mul_i32 s19, s18, s19
	v_mov_b32_e32 v31, s19
	v_mov_b32_e32 v30, 12336
	ds_add_rtn_u32 v31, v30, v31
.LBB0_1103:
	s_or_b64 exec, exec, s[6:7]
.LBB0_1104:
	s_or_b64 exec, exec, s[0:1]
.LBB0_1105:
	v_cndmask_b32_e64 v30, 0, 1, s[30:31]
	v_cmp_ne_u32_e64 s[68:69], 1, v30
	v_and_b32_e32 v30, 0x2000, v8
	s_andn2_b64 vcc, exec, s[30:31]
	v_cmp_ne_u32_e64 s[0:1], 0, v30
	s_cbranch_vccnz .LBB0_1111
	s_and_b64 s[0:1], s[40:41], s[0:1]
	v_cndmask_b32_e64 v32, 0, 1, s[0:1]
	v_cmp_ne_u32_e32 vcc, 0, v32
	s_cmp_lg_u64 vcc, 0
	s_ff1_i32_b64 s0, vcc
	s_cselect_b64 s[6:7], -1, 0
	v_cmp_eq_u32_e64 s[0:1], s0, v0
	v_mov_b32_e32 v26, 0
	s_and_b64 s[6:7], s[6:7], s[0:1]
	s_and_saveexec_b64 s[0:1], s[6:7]
	s_cbranch_execz .LBB0_1110
	s_mov_b64 s[30:31], exec
	v_mbcnt_lo_u32_b32 v26, s30, 0
	v_mbcnt_hi_u32_b32 v26, s31, v26
	s_bcnt1_i32_b64 s18, vcc
	v_cmp_eq_u32_e32 vcc, 0, v26
	s_and_saveexec_b64 s[6:7], vcc
	s_cbranch_execz .LBB0_1109
	s_lshl_b64 s[36:37], s[2:3], 2
	s_add_u32 s36, s92, s36
	s_addc_u32 s37, s93, s37
	s_bcnt1_i32_b64 s19, s[30:31]
	s_mul_i32 s19, s18, s19
	v_mov_b32_e32 v32, s19
	v_mov_b32_e32 v26, 12340
	ds_add_rtn_u32 v26, v26, v32
.LBB0_1109:
	s_or_b64 exec, exec, s[6:7]
.LBB0_1110:
	s_or_b64 exec, exec, s[0:1]
.LBB0_1111:
	v_cndmask_b32_e64 v33, 0, 1, s[8:9]
	v_and_b32_e32 v8, 0x4000, v8
	v_mov_b32_e32 v32, 0
	v_cmp_ne_u32_e64 s[70:71], 1, v33
	s_andn2_b64 vcc, exec, s[8:9]
	v_cmp_ne_u32_e64 s[0:1], 0, v8
	s_cbranch_vccnz .LBB0_1117
	s_and_b64 s[0:1], s[40:41], s[0:1]
	v_cndmask_b32_e64 v33, 0, 1, s[0:1]
	v_cmp_ne_u32_e32 vcc, 0, v33
	s_cmp_lg_u64 vcc, 0
	s_ff1_i32_b64 s0, vcc
	s_cselect_b64 s[6:7], -1, 0
	v_cmp_eq_u32_e64 s[0:1], s0, v0
	v_mov_b32_e32 v32, 0
	s_and_b64 s[6:7], s[6:7], s[0:1]
	s_and_saveexec_b64 s[0:1], s[6:7]
	s_cbranch_execz .LBB0_1116
	s_mov_b64 s[8:9], exec
	v_mbcnt_lo_u32_b32 v32, s8, 0
	v_mbcnt_hi_u32_b32 v32, s9, v32
	s_bcnt1_i32_b64 s18, vcc
	v_cmp_eq_u32_e32 vcc, 0, v32
	s_and_saveexec_b64 s[6:7], vcc
	s_cbranch_execz .LBB0_1115
	s_lshl_b64 s[30:31], s[2:3], 2
	s_add_u32 s30, s92, s30
	s_addc_u32 s31, s93, s31
	s_bcnt1_i32_b64 s8, s[8:9]
	s_mul_i32 s8, s18, s8
	v_mov_b32_e32 v33, s8
	v_mov_b32_e32 v32, 12344
	ds_add_rtn_u32 v32, v32, v33
.LBB0_1115:
	s_or_b64 exec, exec, s[6:7]
.LBB0_1116:
	s_or_b64 exec, exec, s[0:1]
.LBB0_1117:
	s_waitcnt lgkmcnt(0)
	s_barrier
	v_readfirstlane_b32 s32, v211
	s_nop 3
	s_cmp_lt_u32 s32, 64
	s_cbranch_scc0 .Lgate_nolead
	s_lshl_b64 s[100:101], s[2:3], 2
	v_readlane_b32 s32, v253, 15
	s_nop 3
	s_add_u32 s100, s100, s32
	v_readlane_b32 s32, v253, 16
	s_nop 3
	s_addc_u32 s101, s101, s32
	s_mov_b64 exec, 0x7fff
	v_lshlrev_b32_e32 v33, 2, v0
	ds_read_b32 v34, v33 offset:12288
	s_waitcnt lgkmcnt(0)
	v_cmp_ne_u32_e32 vcc, 0, v34
	s_and_b64 exec, exec, vcc
	s_cbranch_execz .Lgate_noadd
	global_atomic_add v34, v33, v34, s[100:101] sc0
	s_waitcnt vmcnt(0)
	ds_write_b32 v33, v34 offset:12352
	s_waitcnt lgkmcnt(0)
.Lgate_noadd:
	s_mov_b64 exec, -1
.Lgate_nolead:
	s_barrier
	v_and_b32_e32 v33, 15, v0
	v_lshlrev_b32_e32 v33, 2, v33
	ds_read_b32 v35, v33 offset:12352
	v_mov_b32_e32 v34, 0
	s_waitcnt lgkmcnt(0)
	ds_write_b32 v33, v34 offset:12288
	v_readlane_b32 s32, v35, 0
	v_readlane_b32 s100, v35, 1
	v_readlane_b32 s101, v35, 2
	v_add_u32_e32 v7, s32, v7
	v_add_u32_e32 v3, s100, v3
	v_add_u32_e32 v12, s101, v12
	v_readlane_b32 s32, v35, 3
	v_readlane_b32 s100, v35, 4
	v_readlane_b32 s101, v35, 5
	v_add_u32_e32 v5, s32, v5
	v_add_u32_e32 v16, s100, v16
	v_add_u32_e32 v10, s101, v10
	v_readlane_b32 s32, v35, 6
	v_readlane_b32 s100, v35, 7
	v_readlane_b32 s101, v35, 8
	v_add_u32_e32 v20, s32, v20
	v_add_u32_e32 v14, s100, v14
	v_add_u32_e32 v24, s101, v24
	v_readlane_b32 s32, v35, 9
	v_readlane_b32 s100, v35, 10
	v_readlane_b32 s101, v35, 11
	v_add_u32_e32 v18, s32, v18
	v_add_u32_e32 v28, s100, v28
	v_add_u32_e32 v22, s101, v22
	v_readlane_b32 s32, v35, 12
	v_readlane_b32 s100, v35, 13
	v_readlane_b32 s101, v35, 14
	v_add_u32_e32 v31, s32, v31
	v_add_u32_e32 v26, s100, v26
	v_add_u32_e32 v32, s101, v32
	v_lshlrev_b64 v[34:35], v0, -1
	v_not_b32_e32 v33, v35
	s_and_b64 vcc, exec, s[42:43]
	v_not_b32_e32 v34, v34
	s_cbranch_vccnz .LBB0_1122
	v_cmp_eq_u32_e32 vcc, 1, v4
	s_and_b64 s[6:7], s[40:41], vcc
	v_cndmask_b32_e64 v0, 0, 1, s[6:7]
	v_cmp_ne_u32_e32 vcc, 0, v0
	s_cbranch_vccz .LBB0_1122
	s_ff1_i32_b64 s0, vcc
	v_or_b32_e32 v0, s0, v2
	v_lshlrev_b32_e32 v0, 2, v0
	ds_bpermute_b32 v0, v0, v7
	s_and_saveexec_b64 s[0:1], s[6:7]
	s_cbranch_execz .LBB0_1121
	s_lshl_b64 s[6:7], s[2:3], 13
	v_readlane_b32 s3, v253, 25
	s_add_u32 s6, s3, s6
	v_readlane_b32 s3, v253, 26
	s_addc_u32 s7, s3, s7
	v_and_b32_e32 v4, vcc_lo, v34
	s_waitcnt lgkmcnt(0)
	v_lshl_add_u64 v[36:37], v[0:1], 1, s[6:7]
	v_and_b32_e32 v0, vcc_hi, v33
	v_bcnt_u32_b32 v4, v4, 0
	v_bcnt_u32_b32 v0, v0, v4
	v_lshlrev_b32_e32 v0, 1, v0
	v_lshl_add_u64 v[36:37], v[36:37], 0, v[0:1]
	global_store_short v[36:37], v54, off

	.amdhsa_kernel _Z4mega6Params
		.amdhsa_group_segment_fixed_size 0
		.amdhsa_private_segment_fixed_size 0
		.amdhsa_kernarg_size 448
		.amdhsa_user_sgpr_count 2
		.amdhsa_user_sgpr_dispatch_ptr 0
		.amdhsa_user_sgpr_queue_ptr 0
		.amdhsa_user_sgpr_kernarg_segment_ptr 1
		.amdhsa_user_sgpr_dispatch_id 0
		.amdhsa_user_sgpr_kernarg_preload_length 0
		.amdhsa_user_sgpr_kernarg_preload_offset 0
		.amdhsa_user_sgpr_private_segment_size 0
		.amdhsa_uses_dynamic_stack 0
		.amdhsa_enable_private_segment 0
		.amdhsa_system_sgpr_workgroup_id_x 1
		.amdhsa_system_sgpr_workgroup_id_y 0
		.amdhsa_system_sgpr_workgroup_id_z 0
		.amdhsa_system_sgpr_workgroup_info 0
		.amdhsa_system_vgpr_workitem_id 2
		.amdhsa_next_free_vgpr 256
		.amdhsa_next_free_sgpr 102
		.amdhsa_accum_offset 256
		.amdhsa_reserve_vcc 1
		.amdhsa_float_round_mode_32 0
		.amdhsa_float_round_mode_16_64 0
		.amdhsa_float_denorm_mode_32 3
		.amdhsa_float_denorm_mode_16_64 3
		.amdhsa_dx10_clamp 1
		.amdhsa_ieee_mode 1
		.amdhsa_fp16_overflow 0
		.amdhsa_tg_split 0
		.amdhsa_exception_fp_ieee_invalid_op 0
		.amdhsa_exception_fp_denorm_src 0
		.amdhsa_exception_fp_ieee_div_zero 0
		.amdhsa_exception_fp_ieee_overflow 0
		.amdhsa_exception_fp_ieee_underflow 0
		.amdhsa_exception_fp_ieee_inexact 0
		.amdhsa_exception_int_div_zero 0
	.end_amdhsa_kernel

amdhsa.kernels:
  - .agpr_count:     0
    .args:
      - .offset:         0
        .size:           192
        .value_kind:     by_value
      - .offset:         192
        .size:           4
        .value_kind:     hidden_block_count_x
      - .offset:         196
        .size:           4
        .value_kind:     hidden_block_count_y
      - .offset:         200
        .size:           4
        .value_kind:     hidden_block_count_z
      - .offset:         204
        .size:           2
        .value_kind:     hidden_group_size_x
      - .offset:         206
        .size:           2
        .value_kind:     hidden_group_size_y
      - .offset:         208
        .size:           2
        .value_kind:     hidden_group_size_z
      - .offset:         210
        .size:           2
        .value_kind:     hidden_remainder_x
      - .offset:         212
        .size:           2
        .value_kind:     hidden_remainder_y
      - .offset:         214
        .size:           2
        .value_kind:     hidden_remainder_z
      - .offset:         232
        .size:           8
        .value_kind:     hidden_global_offset_x
      - .offset:         240
        .size:           8
        .value_kind:     hidden_global_offset_y
      - .offset:         248
        .size:           8
        .value_kind:     hidden_global_offset_z
      - .offset:         256
        .size:           2
        .value_kind:     hidden_grid_dims
      - .offset:         280
        .size:           8
        .value_kind:     hidden_multigrid_sync_arg
      - .offset:         312
        .size:           4
        .value_kind:     hidden_dynamic_lds_size
    .group_segment_fixed_size: 0
    .kernarg_segment_align: 8
    .kernarg_segment_size: 448
    .language:       OpenCL C
    .language_version:
      - 2
      - 0
    .max_flat_workgroup_size: 512
    .name:           _Z4mega6Params
    .private_segment_fixed_size: 0
    .sgpr_count:     108
    .sgpr_spill_count: 275
    .symbol:         _Z4mega6Params.kd
    .uniform_work_group_size: 1
    .uses_dynamic_stack: false
    .vgpr_count:     256
    .vgpr_spill_count: 0
    .wavefront_size: 64
  - .agpr_count:     0
    .args:
      - .address_space:  global
        .offset:         0
        .size:           8
        .value_kind:     global_buffer
      - .offset:         8
        .size:           4
        .value_kind:     by_value
      - .offset:         12
        .size:           4
        .value_kind:     by_value
      - .offset:         16
        .size:           4
        .value_kind:     hidden_block_count_x
      - .offset:         20
        .size:           4
        .value_kind:     hidden_block_count_y
      - .offset:         24
        .size:           4
        .value_kind:     hidden_block_count_z
      - .offset:         28
        .size:           2
        .value_kind:     hidden_group_size_x
      - .offset:         30
        .size:           2
        .value_kind:     hidden_group_size_y
      - .offset:         32
        .size:           2
        .value_kind:     hidden_group_size_z
      - .offset:         34
        .size:           2
        .value_kind:     hidden_remainder_x
      - .offset:         36
        .size:           2
        .value_kind:     hidden_remainder_y
      - .offset:         38
        .size:           2
        .value_kind:     hidden_remainder_z
      - .offset:         56
        .size:           8
        .value_kind:     hidden_global_offset_x
      - .offset:         64
        .size:           8
        .value_kind:     hidden_global_offset_y
      - .offset:         72
        .size:           8
        .value_kind:     hidden_global_offset_z
      - .offset:         80
        .size:           2
        .value_kind:     hidden_grid_dims
    .group_segment_fixed_size: 0
    .kernarg_segment_align: 8
    .kernarg_segment_size: 272
    .language:       OpenCL C
    .language_version:
      - 2
      - 0
    .max_flat_workgroup_size: 1024
    .name:           _Z9fill_diagPfif
    .private_segment_fixed_size: 0
    .sgpr_count:     16
    .sgpr_spill_count: 0
    .symbol:         _Z9fill_diagPfif.kd
    .uniform_work_group_size: 1
    .uses_dynamic_stack: false
    .vgpr_count:     6
    .vgpr_spill_count: 0
    .wavefront_size: 64
